# HGRN2 head start: the 64 HGRN2 workgroups run their first 12 / 20 chunks during the conv and gated-delta-precompute phases (done by the other 192 workgroups); chain suspended/resumed across the two gr
# speedup vs baseline: 1.0360x; 1.0039x over previous
_Z4mega6Params:
	s_mov_b64 s[66:67], s[0:1]
	s_load_dwordx2 s[68:69], s[0:1], 0x100
	s_add_u32 s0, s66, 0x108
	s_addc_u32 s1, s67, 0
	v_and_b32_e32 v236, 0x3ff, v0
	v_writelane_b32 v255, s0, 0
	s_mov_b32 s62, s2
	s_mov_b32 s100, 0
	v_cmp_gt_u32_e32 vcc, 16, v236
	v_writelane_b32 v255, s1, 1
	s_and_saveexec_b64 s[4:5], vcc
	v_lshl_add_u32 v1, v236, 2, 0
	v_add_u32_e32 v1, 0x23fc0, v1
	v_mov_b32_e32 v2, 0
	ds_write_b32 v1, v2
	s_or_b64 exec, exec, s[4:5]
	s_cmp_lg_u32 s62, 0
	s_waitcnt lgkmcnt(0)
	s_barrier
	s_cbranch_scc0 .LBB0_4
	s_lshl_b32 s3, s68, 1
	s_lshl_b32 s63, s69, 1
	s_cmp_ge_i32 s3, s63
	s_cbranch_scc0 .LBB0_7
	s_getpc_b64 s[98:99]

.LBB0_15:
	s_mov_b64 s[80:81], s[66:67]
	v_mov_b32_e32 v186, v236
	s_mov_b32 s64, s62
	s_load_dword s75, s[66:67], 0x108
	s_waitcnt lgkmcnt(0)
	s_load_dwordx2 s[78:79], s[80:81], 0xf8
	s_memrealtime s[4:5]
	v_writelane_b32 v255, s2, 22
	s_movk_i32 s101, 0x7fff
	s_cmp_eq_u32 s2, 3
	s_cbranch_scc1 .Lhs_p2
	s_cmp_eq_u32 s2, 14
	s_cbranch_scc1 .Lhs_p2
	s_cmp_eq_u32 s2, 4
	s_cbranch_scc1 .Lhs_p3
	s_cmp_eq_u32 s2, 15
	s_cbranch_scc1 .Lhs_p3
	s_branch .Lhs_done
.Lhs_p2:
	s_movk_i32 s101, 12
	s_branch .Lhs_adj
.Lhs_p3:
	s_movk_i32 s101, 20
.Lhs_adj:
	s_cmp_lt_u32 s62, 64
	s_cbranch_scc1 .Lhs_done
	s_sub_u32 s64, s62, 64
	s_movk_i32 s75, 0xc0
.Lhs_done:
	s_cmp_gt_u32 s3, 1
	s_waitcnt lgkmcnt(0)
	s_mov_b64 s[4:5], -1
	s_cbranch_scc1 .LBB0_16
	s_getpc_b64 s[98:99]

.LBB0_336:
	s_andn2_b64 vcc, exec, s[4:5]
	s_cbranch_vccnz .LBB0_911
	v_readlane_b32 s0, v255, 25
	s_cmp_lt_u32 s62, 64
	s_cbranch_scc0 .Lhs_nored
	s_cmp_eq_u32 s0, 2
	s_cbranch_scc1 .Lhs_red
	s_cmp_eq_u32 s0, 3
	s_cbranch_scc0 .Lhs_nored
.Lhs_red:
	s_mov_b64 s[4:5], -1
	s_branch .Lhs_mix
.Lhs_nored:
	s_cmp_lt_i32 s0, 2
	s_mov_b64 s[4:5], -1
	s_cbranch_scc1 .LBB0_658
	v_readlane_b32 s0, v255, 25
	s_cmp_lt_i32 s0, 3
	s_cbranch_scc1 .LBB0_622
	v_readlane_b32 s0, v255, 25
	s_cmp_gt_i32 s0, 3
	s_cbranch_scc0 .LBB0_567
.Lhs_mix:
	v_writelane_b32 v255, s63, 26
	v_writelane_b32 v255, s62, 27
	s_cmpk_gt_i32 s64, 0xff
	s_movk_i32 s63, 0xe00
	v_readlane_b32 s58, v255, 3
	v_readlane_b32 s72, v255, 5
	s_cbranch_scc1 .LBB0_566
	v_readlane_b32 s0, v255, 23
	s_lshl_b32 s1, s0, 5
	v_writelane_b32 v255, s1, 28
	s_lshl_b32 s1, s0, 4
	s_lshl_b32 s0, s0, 3
	s_add_u32 s82, s78, 0x8285000
	v_writelane_b32 v255, s1, 29
	s_addc_u32 s83, s79, 0
	v_writelane_b32 v255, s0, 30
	s_add_u32 s0, s78, 0x33dd000
	v_writelane_b32 v255, s0, 31
	s_addc_u32 s0, s79, 0
	s_add_u32 s84, s78, 0x3e85000
	s_addc_u32 s85, s79, 0
	s_add_u32 s86, s78, 0x3c65000
	v_writelane_b32 v255, s0, 32
	s_addc_u32 s87, s79, 0
	s_mov_b32 s65, s64
	s_branch .LBB0_343

.LBB0_454:
	s_andn2_b64 vcc, exec, s[4:5]
	s_cbranch_vccnz .LBB0_342
	s_cmp_eq_u32 s36, 1
	s_mov_b64 s[4:5], -1
	s_cbranch_scc1 .LBB0_542
	s_cmp_eq_u32 s100, 1
	s_cbranch_scc1 .Lhs_resume
	s_movk_i32 s0, 0x800
	v_readfirstlane_b32 s1, v68
	v_cmp_gt_i32_e32 vcc, s0, v68
	s_and_saveexec_b64 s[8:9], vcc
	s_movk_i32 s2, 0x4bf
	s_movk_i32 s38, 0xff00
	s_cbranch_execz .LBB0_464
	s_waitcnt vmcnt(5)
	v_max_i32_e32 v4, 0x600, v68
	v_sub_u32_e32 v4, v4, v68
	v_add_u32_e32 v5, 0x1ff, v4
	s_movk_i32 s0, 0x1ff
	v_cmp_lt_u32_e32 vcc, s0, v5
	v_mov_b32_e32 v4, v68
	s_and_saveexec_b64 s[10:11], vcc
	s_cbranch_execz .LBB0_461
	v_lshrrev_b32_e32 v4, 9, v5
	v_add_u32_e32 v6, 1, v4
	v_and_b32_e32 v7, 0xfffffe, v6
	v_add_u32_e32 v69, 0x200, v68
	s_waitcnt lgkmcnt(0)
	s_mov_b64 s[12:13], 0
	s_waitcnt vmcnt(4)
	v_mov_b32_e32 v8, v7
	v_mov_b64_e32 v[4:5], v[68:69]

.Lhs_suspend:
	s_waitcnt vmcnt(0) lgkmcnt(0)
	v_mov_b32_e32 v122, v4
	v_mov_b32_e32 v123, v5
	v_mov_b32_e32 v124, v6
	v_mov_b32_e32 v125, v7
	v_mov_b32_e32 v126, v8
	v_mov_b32_e32 v127, v9
	v_mov_b32_e32 v128, v10
	v_mov_b32_e32 v129, v11
	v_mov_b32_e32 v130, v12
	v_mov_b32_e32 v131, v13
	v_mov_b32_e32 v132, v14
	v_mov_b32_e32 v133, v15
	v_mov_b32_e32 v134, v16
	v_mov_b32_e32 v135, v17
	v_mov_b32_e32 v136, v18
	v_mov_b32_e32 v137, v19
	v_mov_b32_e32 v138, v20
	v_writelane_b32 v140, s0, 0
	v_writelane_b32 v140, s1, 1
	v_writelane_b32 v140, s2, 2
	v_writelane_b32 v140, s3, 3
	v_writelane_b32 v140, s4, 4
	v_writelane_b32 v140, s5, 5
	v_writelane_b32 v140, s6, 6
	v_writelane_b32 v140, s7, 7
	v_writelane_b32 v140, s8, 8
	v_writelane_b32 v140, s9, 9
	v_writelane_b32 v140, s10, 10
	v_writelane_b32 v140, s11, 11
	v_writelane_b32 v140, s12, 12
	v_writelane_b32 v140, s13, 13
	v_writelane_b32 v140, s14, 14
	v_writelane_b32 v140, s15, 15
	v_writelane_b32 v140, s16, 16
	v_writelane_b32 v140, s17, 17
	v_writelane_b32 v140, s18, 18
	v_writelane_b32 v140, s19, 19
	v_writelane_b32 v140, s20, 20
	v_writelane_b32 v140, s21, 21
	v_writelane_b32 v140, s22, 22
	v_writelane_b32 v140, s23, 23
	v_writelane_b32 v140, s24, 24
	v_writelane_b32 v140, s25, 25
	v_writelane_b32 v140, s26, 26
	v_writelane_b32 v140, s27, 27
	v_writelane_b32 v140, s28, 28
	v_writelane_b32 v140, s29, 29
	v_writelane_b32 v140, s30, 30
	v_writelane_b32 v140, s31, 31
	v_writelane_b32 v140, s32, 32
	v_writelane_b32 v140, s33, 33
	v_writelane_b32 v140, s34, 34
	v_writelane_b32 v140, s35, 35
	v_writelane_b32 v140, s36, 36
	v_writelane_b32 v140, s37, 37
	v_writelane_b32 v140, s38, 38
	v_writelane_b32 v140, s39, 39
	v_writelane_b32 v140, s40, 40
	v_writelane_b32 v140, s41, 41
	v_writelane_b32 v140, s42, 42
	v_writelane_b32 v140, s43, 43
	v_writelane_b32 v140, s44, 44
	v_writelane_b32 v140, s45, 45
	v_writelane_b32 v140, s46, 46
	v_writelane_b32 v140, s47, 47
	v_writelane_b32 v140, s48, 48
	v_writelane_b32 v140, s49, 49
	v_writelane_b32 v140, s50, 50
	v_writelane_b32 v140, s51, 51
	v_writelane_b32 v140, s52, 52
	v_writelane_b32 v140, s53, 53
	v_writelane_b32 v140, s54, 54
	v_writelane_b32 v140, s55, 55
	v_writelane_b32 v140, s56, 56
	v_writelane_b32 v140, s57, 57
	v_writelane_b32 v140, s58, 58
	v_writelane_b32 v140, s59, 59
	v_writelane_b32 v140, s60, 60
	v_writelane_b32 v140, s61, 61
	v_writelane_b32 v140, s62, 62
	v_writelane_b32 v140, s63, 63
	v_writelane_b32 v141, s64, 0
	v_writelane_b32 v141, s65, 1
	v_writelane_b32 v141, s66, 2
	v_writelane_b32 v141, s67, 3
	v_writelane_b32 v141, s68, 4
	v_writelane_b32 v141, s69, 5
	v_writelane_b32 v141, s70, 6
	v_writelane_b32 v141, s71, 7
	v_writelane_b32 v141, s72, 8
	v_writelane_b32 v141, s73, 9
	v_writelane_b32 v141, s74, 10
	v_writelane_b32 v141, s75, 11
	v_writelane_b32 v141, s76, 12
	v_writelane_b32 v141, s77, 13
	v_writelane_b32 v141, s78, 14
	v_writelane_b32 v141, s79, 15
	v_writelane_b32 v141, s80, 16
	v_writelane_b32 v141, s81, 17
	v_writelane_b32 v141, s82, 18
	v_writelane_b32 v141, s83, 19
	v_writelane_b32 v141, s84, 20
	v_writelane_b32 v141, s85, 21
	v_writelane_b32 v141, s86, 22
	v_writelane_b32 v141, s87, 23
	v_writelane_b32 v141, s88, 24
	v_writelane_b32 v141, s89, 25
	v_writelane_b32 v141, s90, 26
	v_writelane_b32 v141, s91, 27
	v_writelane_b32 v141, s92, 28
	v_writelane_b32 v141, s93, 29
	v_writelane_b32 v141, s94, 30
	v_writelane_b32 v141, s95, 31
	v_writelane_b32 v141, s96, 32
	v_writelane_b32 v141, s97, 33
	v_writelane_b32 v141, s98, 34
	v_writelane_b32 v141, s99, 35
	s_mov_b32 s100, 1
	s_branch .LBB0_541
.Lhs_resume:
	v_mov_b32_e32 v4, v122
	v_mov_b32_e32 v5, v123
	v_mov_b32_e32 v6, v124
	v_mov_b32_e32 v7, v125
	v_mov_b32_e32 v8, v126
	v_mov_b32_e32 v9, v127
	v_mov_b32_e32 v10, v128
	v_mov_b32_e32 v11, v129
	v_mov_b32_e32 v12, v130
	v_mov_b32_e32 v13, v131
	v_mov_b32_e32 v14, v132
	v_mov_b32_e32 v15, v133
	v_mov_b32_e32 v16, v134
	v_mov_b32_e32 v17, v135
	v_mov_b32_e32 v18, v136
	v_mov_b32_e32 v19, v137
	v_mov_b32_e32 v20, v138
	v_readlane_b32 s0, v140, 0
	v_readlane_b32 s1, v140, 1
	v_readlane_b32 s2, v140, 2
	v_readlane_b32 s4, v140, 4
	v_readlane_b32 s5, v140, 5
	v_readlane_b32 s6, v140, 6
	v_readlane_b32 s7, v140, 7
	v_readlane_b32 s8, v140, 8
	v_readlane_b32 s9, v140, 9
	v_readlane_b32 s10, v140, 10
	v_readlane_b32 s11, v140, 11
	v_readlane_b32 s12, v140, 12
	v_readlane_b32 s13, v140, 13
	v_readlane_b32 s14, v140, 14
	v_readlane_b32 s15, v140, 15
	v_readlane_b32 s16, v140, 16
	v_readlane_b32 s17, v140, 17
	v_readlane_b32 s18, v140, 18
	v_readlane_b32 s19, v140, 19
	v_readlane_b32 s20, v140, 20
	v_readlane_b32 s21, v140, 21
	v_readlane_b32 s22, v140, 22
	v_readlane_b32 s23, v140, 23
	v_readlane_b32 s24, v140, 24
	v_readlane_b32 s25, v140, 25
	v_readlane_b32 s26, v140, 26
	v_readlane_b32 s27, v140, 27
	v_readlane_b32 s28, v140, 28
	v_readlane_b32 s29, v140, 29
	v_readlane_b32 s30, v140, 30
	v_readlane_b32 s31, v140, 31
	v_readlane_b32 s32, v140, 32
	v_readlane_b32 s33, v140, 33
	v_readlane_b32 s34, v140, 34
	v_readlane_b32 s35, v140, 35
	v_readlane_b32 s36, v140, 36
	v_readlane_b32 s37, v140, 37
	v_readlane_b32 s38, v140, 38
	v_readlane_b32 s39, v140, 39
	v_readlane_b32 s40, v140, 40
	v_readlane_b32 s41, v140, 41
	v_readlane_b32 s42, v140, 42
	v_readlane_b32 s43, v140, 43
	v_readlane_b32 s44, v140, 44
	v_readlane_b32 s45, v140, 45
	v_readlane_b32 s46, v140, 46
	v_readlane_b32 s47, v140, 47
	v_readlane_b32 s48, v140, 48
	v_readlane_b32 s49, v140, 49
	v_readlane_b32 s50, v140, 50
	v_readlane_b32 s51, v140, 51
	v_readlane_b32 s52, v140, 52
	v_readlane_b32 s53, v140, 53
	v_readlane_b32 s54, v140, 54
	v_readlane_b32 s55, v140, 55
	v_readlane_b32 s56, v140, 56
	v_readlane_b32 s57, v140, 57
	v_readlane_b32 s58, v140, 58
	v_readlane_b32 s59, v140, 59
	v_readlane_b32 s60, v140, 60
	v_readlane_b32 s61, v140, 61
	v_readlane_b32 s62, v140, 62
	v_readlane_b32 s63, v140, 63
	v_readlane_b32 s64, v141, 0
	v_readlane_b32 s65, v141, 1
	v_readlane_b32 s66, v141, 2
	v_readlane_b32 s67, v141, 3
	v_readlane_b32 s68, v141, 4
	v_readlane_b32 s69, v141, 5
	v_readlane_b32 s70, v141, 6
	v_readlane_b32 s71, v141, 7
	v_readlane_b32 s72, v141, 8
	v_readlane_b32 s73, v141, 9
	v_readlane_b32 s74, v141, 10
	v_readlane_b32 s75, v141, 11
	v_readlane_b32 s76, v141, 12
	v_readlane_b32 s77, v141, 13
	v_readlane_b32 s78, v141, 14
	v_readlane_b32 s79, v141, 15
	v_readlane_b32 s80, v141, 16
	v_readlane_b32 s81, v141, 17
	v_readlane_b32 s82, v141, 18
	v_readlane_b32 s83, v141, 19
	v_readlane_b32 s84, v141, 20
	v_readlane_b32 s85, v141, 21
	v_readlane_b32 s86, v141, 22
	v_readlane_b32 s87, v141, 23
	v_readlane_b32 s88, v141, 24
	v_readlane_b32 s89, v141, 25
	v_readlane_b32 s90, v141, 26
	v_readlane_b32 s91, v141, 27
	v_readlane_b32 s92, v141, 28
	v_readlane_b32 s93, v141, 29
	v_readlane_b32 s94, v141, 30
	v_readlane_b32 s95, v141, 31
	v_readlane_b32 s96, v141, 32
	v_readlane_b32 s97, v141, 33
	v_readlane_b32 s98, v141, 34
	v_readlane_b32 s99, v141, 35
	s_mov_b32 s100, 0
	s_nop 7
	s_branch .LBB0_481

.LBB0_481:
	s_cmp_ge_u32 s47, s101
	s_cbranch_scc1 .Lhs_suspend
	v_mov_b32_e32 v36, v68
	s_andn2_b64 vcc, exec, s[94:95]
	v_lshrrev_b32_e32 v37, 3, v36
	v_and_or_b32 v40, v37, 7, s70
	v_and_b32_e32 v41, 7, v36
	v_lshlrev_b32_e32 v36, 8, v40
	v_lshlrev_b32_e32 v37, 5, v41
	v_add3_u32 v36, s69, v36, v37
	ds_read_b128 v[44:47], v36
	ds_read_b128 v[36:39], v36 offset:16
	v_mul_lo_u32 v110, v40, s61
	v_lshlrev_b32_e32 v111, 4, v41
	v_cndmask_b32_e64 v40, 0, 1, s[94:95]
	v_lshlrev_b32_e32 v109, 3, v41
	v_add3_u32 v108, 0, v110, v111
	v_cmp_ne_u32_e64 s[34:35], 1, v40
	v_mov_b32_e32 v43, 0
	v_mov_b32_e32 v42, 0
	v_mov_b32_e32 v41, 0
	v_mov_b32_e32 v40, 0
	v_mov_b32_e32 v51, 0
	v_mov_b32_e32 v50, 0
	v_mov_b32_e32 v49, 0
	v_mov_b32_e32 v48, 0
	s_waitcnt vmcnt(7)
	ds_write_b128 v108, v[12:15] offset:27648
	s_cbranch_vccnz .LBB0_483
	v_lshl_add_u32 v40, v109, 2, s66
	ds_read_b128 v[48:51], v40
	ds_read_b128 v[40:43], v40 offset:16
